# norm2_dyn all-G-units-done sweep: s_sleep 127 -> 16 (shorter wake-up delay before conv_ffn)
# baseline (speedup 1.0000x reference)
.LBB0_2158:
	s_or_b64 exec, exec, s[12:13]
	s_xor_b64 s[10:11], s[10:11], -1
	v_cndmask_b32_e64 v2, 0, 1, s[10:11]
	v_cmp_ne_u32_e32 vcc, 0, v2
	s_cbranch_vccz .LBB0_2152
	s_add_i32 s22, s22, 1
	s_and_b32 s10, s22, 15
	s_cmp_lg_u32 s10, 0
	s_mov_b64 s[10:11], -1
	s_sleep 16
	s_cbranch_scc1 .LBB0_2153
	global_load_dword v2, v65, s[16:17] sc1
	s_mov_b64 s[10:11], 0
	s_waitcnt vmcnt(0)
	v_cmp_ne_u32_e32 vcc, 0, v2
	s_cbranch_vccnz .LBB0_2153
	s_cmpk_lt_u32 s22, 0x4001
	s_cselect_b64 s[10:11], -1, 0
	s_nor_b64 s[14:15], s[6:7], s[10:11]
	s_and_saveexec_b64 s[12:13], s[14:15]
	s_cbranch_execz .LBB0_2165
	s_mov_b64 s[18:19], exec
	v_mbcnt_lo_u32_b32 v2, s18, 0
	v_mbcnt_hi_u32_b32 v2, s19, v2
	v_cmp_eq_u32_e32 vcc, 0, v2
	s_and_saveexec_b64 s[14:15], vcc
	s_cbranch_execz .LBB0_2164
	s_bcnt1_i32_b64 s18, s[18:19]
	v_mov_b32_e32 v2, s18
	global_atomic_add v65, v2, s[16:17]
